# P4 order chosen by CU-slot role (first/second resident block) so co-resident blocks alternate GEMM-first / scan-first
# baseline (speedup 1.0000x reference)
_Z11mega_kernelILb1EEv6Paramsii:
	s_load_dwordx2 s[100:101], s[0:1], 0x198
	s_load_dword s3, s[0:1], 0x228
	s_load_dwordx2 s[4:5], s[0:1], 0x68
	s_load_dwordx2 s[6:7], s[0:1], 0xb0
	s_load_dwordx2 s[8:9], s[0:1], 0xb8
	s_load_dwordx2 s[10:11], s[0:1], 0xd8
	s_load_dwordx8 s[24:31], s[0:1], 0x18
	s_load_dwordx2 s[34:35], s[0:1], 0x108
	v_and_b32_e32 v1, 0x3ff, v0
	v_lshrrev_b32_e32 v2, 6, v1
	v_and_b32_e32 v3, 63, v1
	v_lshlrev_b32_e32 v2, 12, v2
	v_lshl_or_b32 v2, v3, 4, v2
	v_and_b32_e32 v3, 31, v1
	v_lshrrev_b32_e32 v4, 5, v1
	v_lshlrev_b32_e32 v3, 4, v3
	s_waitcnt lgkmcnt(0)
	s_cmp_eq_u32 s3, 0x200
	s_cselect_b32 s20, 1, 0
	v_writelane_b32 v255, s20, 46
	s_cbranch_scc0 .Lcc_skip
	s_movk_i32 s20, 0x200
	s_cmpk_lt_u32 s2, 0x180
	s_cselect_b32 s20, 0x400, s20
	s_add_u32 s20, s20, s2
	s_sub_u32 s21, s20, 0x380
	s_lshl_b32 s21, s21, 8
	v_add_u32_e32 v6, s21, v1
	s_cmpk_lt_u32 s20, 0x480
	s_cbranch_scc1 .LccA0
	s_cmpk_lt_u32 s20, 0x580
	s_cbranch_scc1 .LccB0
	s_cmpk_lt_u32 s20, 0x980
	s_cbranch_scc1 .LccC0
	v_add_u32_e32 v6, 0xfffa0000, v6
	v_and_b32_e32 v7, 0xff, v6
	v_bfe_u32 v8, v6, 8, 7
	v_bfe_u32 v9, v6, 15, 2
	v_lshl_or_b32 v8, v7, 9, v8
	v_lshl_or_b32 v8, v9, 7, v8
	v_and_b32_e32 v10, 0xfffe0000, v6
	v_or_b32_e32 v8, v8, v10
	v_lshlrev_b32_e32 v8, 2, v8
	global_load_dword v130, v8, s[30:31]
	s_branch .LccE0

.Lcc_skip:
	s_getreg_b32 s20, hwreg(HW_REG_XCC_ID, 0, 4)
	s_getreg_b32 s21, hwreg(HW_REG_HW_ID)
	s_bfe_u32 s21, s21, 0x80008
	s_lshl_b32 s32, s20, 8
	s_or_b32 s32, s32, s21
	s_mul_hi_u32 s33, s32, 0x4104105
	s_add_u32 s32, s32, s33
	s_add_u32 s32, s32, 1
	s_lshl_b32 s32, s32, 2
	v_cmp_eq_u32_e32 vcc, 0, v1
	s_and_saveexec_b64 s[36:37], vcc
	v_mov_b32_e32 v109, s32
	v_mov_b32_e32 v110, 1
	global_atomic_add v111, v109, v110, s[34:35] sc0
	s_mov_b64 exec, s[36:37]
	s_mov_b32 s12, s2

.Lwc_done:
	s_load_dwordx4 s[72:75], s[0:1], 0x100
	s_mov_b32 s55, s2
	v_and_b32_e32 v250, 0x3ff, v0
	v_cmp_eq_u32_e64 s[4:5], 0, v250
	s_mov_b64 s[2:3], exec
	s_nop 0
	v_writelane_b32 v254, s4, 0
	s_nop 1
	v_writelane_b32 v254, s5, 1
	s_and_b64 s[4:5], s[2:3], s[4:5]
	s_mov_b64 exec, s[4:5]
	s_cbranch_execz .LBB0_2
	v_mov_b32_e32 v2, 0
	v_mov_b32_e32 v3, v2
	v_min_u32_e32 v4, 1, v111
	v_mov_b32_e32 v5, v2
	v_mov_b32_e32 v1, 0x10000
	ds_write_b128 v1, v[2:5]
.LBB0_2:
	s_or_b64 exec, exec, s[2:3]
	s_waitcnt lgkmcnt(0)
	s_barrier
	v_mov_b32_e32 v112, 0x10008
	ds_read_b32 v111, v112
	s_waitcnt lgkmcnt(0)
	v_readfirstlane_b32 s2, v111
	s_nop 3
	v_writelane_b32 v255, s2, 45
	s_getreg_b32 s2, hwreg(HW_REG_XCC_ID, 0, 4)
	s_and_b32 s93, s2, 15
	s_mov_b64 s[2:3], exec
	v_readlane_b32 s4, v254, 0
	v_readlane_b32 s5, v254, 1
	s_and_b64 s[4:5], s[2:3], s[4:5]
	s_mov_b64 exec, s[4:5]
	s_cbranch_execz .LBB0_5
	s_mov_b64 s[4:5], exec
	v_mbcnt_lo_u32_b32 v1, s4, 0
	v_mbcnt_hi_u32_b32 v1, s5, v1
	v_cmp_eq_u32_e32 vcc, 0, v1
	s_and_b64 s[6:7], exec, vcc
	s_mov_b64 exec, s[6:7]
	s_cbranch_execz .LBB0_5
	s_lshl_b32 s6, s93, 8
	s_bcnt1_i32_b64 s4, s[4:5]
	v_mov_b32_e32 v1, s6
	v_mov_b32_e32 v2, s4
	global_atomic_add v1, v2, s[74:75] offset:1024

.LBB0_449:
	s_or_b64 exec, exec, s[0:1]
	v_writelane_b32 v253, s76, 42
	s_cmpk_gt_i32 s55, 0x23f
	s_waitcnt lgkmcnt(0)
	v_writelane_b32 v253, s77, 43
	v_writelane_b32 v253, s78, 44
	v_writelane_b32 v253, s79, 45
	v_writelane_b32 v253, s80, 46
	v_writelane_b32 v253, s81, 47
	v_writelane_b32 v253, s82, 48
	v_writelane_b32 v253, s83, 49
	s_barrier
	s_cbranch_scc1 .LBB0_494
	v_readlane_b32 s98, v255, 45
	s_nop 1
	s_cmp_eq_u32 s98, 1
	s_cselect_b32 s98, 1, 0
	v_writelane_b32 v255, s98, 47
	s_cbranch_scc1 .LBB0_494
